# v7 + code placement: the 12 GEMM K-loop heads and the attention tile body aligned to 64 bytes (s_nop fill)
# baseline (speedup 1.0000x reference)
.LBB0_37:
	s_add_u32 s21, s10, 0x100
	v_mov_b32_e32 v0, 0
	s_addc_u32 s90, s11, 0
	s_mov_b32 s22, -2
	v_mov_b32_e32 v1, v0
	v_mov_b32_e32 v2, v0
	v_mov_b32_e32 v3, v0
	v_mov_b32_e32 v4, v0
	v_mov_b32_e32 v5, v0
	v_mov_b32_e32 v6, v0
	v_mov_b32_e32 v7, v0
	v_mov_b32_e32 v16, v0
	v_mov_b32_e32 v17, v0
	v_mov_b32_e32 v18, v0
	v_mov_b32_e32 v19, v0
	v_mov_b32_e32 v20, v0
	v_mov_b32_e32 v21, v0
	v_mov_b32_e32 v22, v0
	v_mov_b32_e32 v23, v0
	v_mov_b32_e32 v32, v0
	v_mov_b32_e32 v33, v0
	v_mov_b32_e32 v34, v0
	v_mov_b32_e32 v35, v0
	v_mov_b32_e32 v36, v0
	v_mov_b32_e32 v37, v0
	v_mov_b32_e32 v38, v0
	v_mov_b32_e32 v39, v0
	v_mov_b32_e32 v48, v0
	v_mov_b32_e32 v49, v0
	v_mov_b32_e32 v50, v0
	v_mov_b32_e32 v51, v0
	v_mov_b32_e32 v52, v0
	v_mov_b32_e32 v53, v0
	v_mov_b32_e32 v54, v0
	v_mov_b32_e32 v55, v0
	v_mov_b32_e32 v8, v0
	v_mov_b32_e32 v9, v0
	v_mov_b32_e32 v10, v0
	v_mov_b32_e32 v11, v0
	v_mov_b32_e32 v12, v0
	v_mov_b32_e32 v13, v0
	v_mov_b32_e32 v14, v0
	v_mov_b32_e32 v15, v0
	v_mov_b32_e32 v24, v0
	v_mov_b32_e32 v25, v0
	v_mov_b32_e32 v26, v0
	v_mov_b32_e32 v27, v0
	v_mov_b32_e32 v28, v0
	v_mov_b32_e32 v29, v0
	v_mov_b32_e32 v30, v0
	v_mov_b32_e32 v31, v0
	v_mov_b32_e32 v40, v0
	v_mov_b32_e32 v41, v0
	v_mov_b32_e32 v42, v0
	v_mov_b32_e32 v43, v0
	v_mov_b32_e32 v44, v0
	v_mov_b32_e32 v45, v0
	v_mov_b32_e32 v46, v0
	v_mov_b32_e32 v47, v0
	v_mov_b32_e32 v56, v0
	v_mov_b32_e32 v57, v0
	v_mov_b32_e32 v58, v0
	v_mov_b32_e32 v59, v0
	v_mov_b32_e32 v60, v0
	v_mov_b32_e32 v61, v0
	v_mov_b32_e32 v62, v0
	v_mov_b32_e32 v63, v0
	v_mov_b32_e32 v64, v0
	v_mov_b32_e32 v65, v0
	v_mov_b32_e32 v66, v0
	v_mov_b32_e32 v67, v0
	v_mov_b32_e32 v68, v0
	v_mov_b32_e32 v69, v0
	v_mov_b32_e32 v70, v0
	v_mov_b32_e32 v71, v0
	v_mov_b32_e32 v80, v0
	v_mov_b32_e32 v81, v0
	v_mov_b32_e32 v82, v0
	v_mov_b32_e32 v83, v0
	v_mov_b32_e32 v84, v0
	v_mov_b32_e32 v85, v0
	v_mov_b32_e32 v86, v0
	v_mov_b32_e32 v87, v0
	v_mov_b32_e32 v96, v0
	v_mov_b32_e32 v97, v0
	v_mov_b32_e32 v98, v0
	v_mov_b32_e32 v99, v0
	v_mov_b32_e32 v100, v0
	v_mov_b32_e32 v101, v0
	v_mov_b32_e32 v102, v0
	v_mov_b32_e32 v103, v0
	v_mov_b32_e32 v112, v0
	v_mov_b32_e32 v113, v0
	v_mov_b32_e32 v114, v0
	v_mov_b32_e32 v115, v0
	v_mov_b32_e32 v116, v0
	v_mov_b32_e32 v117, v0
	v_mov_b32_e32 v118, v0
	v_mov_b32_e32 v119, v0
	v_mov_b32_e32 v72, v0
	v_mov_b32_e32 v73, v0
	v_mov_b32_e32 v74, v0
	v_mov_b32_e32 v75, v0
	v_mov_b32_e32 v76, v0
	v_mov_b32_e32 v77, v0
	v_mov_b32_e32 v78, v0
	v_mov_b32_e32 v79, v0
	v_mov_b32_e32 v88, v0
	v_mov_b32_e32 v89, v0
	v_mov_b32_e32 v90, v0
	v_mov_b32_e32 v91, v0
	v_mov_b32_e32 v92, v0
	v_mov_b32_e32 v93, v0
	v_mov_b32_e32 v94, v0
	v_mov_b32_e32 v95, v0
	v_mov_b32_e32 v104, v0
	v_mov_b32_e32 v105, v0
	v_mov_b32_e32 v106, v0
	v_mov_b32_e32 v107, v0
	v_mov_b32_e32 v108, v0
	v_mov_b32_e32 v109, v0
	v_mov_b32_e32 v110, v0
	v_mov_b32_e32 v111, v0
	v_mov_b32_e32 v120, v0
	v_mov_b32_e32 v121, v0
	v_mov_b32_e32 v122, v0
	v_mov_b32_e32 v123, v0
	v_mov_b32_e32 v124, v0
	v_mov_b32_e32 v125, v0
	v_mov_b32_e32 v126, v0
	v_mov_b32_e32 v127, v0
	.p2alignl 6, 3212836864

.LBB0_55:
	s_ashr_i32 s37, s36, 31
	s_lshl_b64 s[14:15], s[36:37], 19
	s_add_u32 s44, s24, s14
	s_addc_u32 s45, s25, s15
	s_and_b64 s[14:15], s[38:39], exec
	s_cselect_b32 s20, s45, s13
	s_cselect_b32 s37, s44, s12
	s_ashr_i32 s41, s40, 31
	s_lshl_b64 s[14:15], s[40:41], 19
	s_add_u32 s92, s26, s14
	s_addc_u32 s93, s27, s15
	s_and_b64 s[14:15], s[38:39], exec
	s_cselect_b32 s41, s93, s11
	s_cselect_b32 s91, s92, s10
	s_add_u32 s96, s10, 0x100
	s_addc_u32 s21, s11, 0
	s_add_u32 s10, s12, 0x40080
	v_mov_b32_e32 v4, 0
	s_addc_u32 s11, s13, 0
	s_mov_b32 s22, -2
	v_mov_b32_e32 v5, v4
	v_mov_b32_e32 v6, v4
	v_mov_b32_e32 v7, v4
	v_mov_b32_e32 v8, v4
	v_mov_b32_e32 v9, v4
	v_mov_b32_e32 v10, v4
	v_mov_b32_e32 v11, v4
	v_mov_b32_e32 v20, v4
	v_mov_b32_e32 v21, v4
	v_mov_b32_e32 v22, v4
	v_mov_b32_e32 v23, v4
	v_mov_b32_e32 v24, v4
	v_mov_b32_e32 v25, v4
	v_mov_b32_e32 v26, v4
	v_mov_b32_e32 v27, v4
	v_mov_b32_e32 v36, v4
	v_mov_b32_e32 v37, v4
	v_mov_b32_e32 v38, v4
	v_mov_b32_e32 v39, v4
	v_mov_b32_e32 v40, v4
	v_mov_b32_e32 v41, v4
	v_mov_b32_e32 v42, v4
	v_mov_b32_e32 v43, v4
	v_mov_b32_e32 v52, v4
	v_mov_b32_e32 v53, v4
	v_mov_b32_e32 v54, v4
	v_mov_b32_e32 v55, v4
	v_mov_b32_e32 v56, v4
	v_mov_b32_e32 v57, v4
	v_mov_b32_e32 v58, v4
	v_mov_b32_e32 v59, v4
	v_mov_b32_e32 v0, v4
	v_mov_b32_e32 v1, v4
	v_mov_b32_e32 v2, v4
	v_mov_b32_e32 v3, v4
	v_mov_b32_e32 v12, v4
	v_mov_b32_e32 v13, v4
	v_mov_b32_e32 v14, v4
	v_mov_b32_e32 v15, v4
	v_mov_b32_e32 v16, v4
	v_mov_b32_e32 v17, v4
	v_mov_b32_e32 v18, v4
	v_mov_b32_e32 v19, v4
	v_mov_b32_e32 v28, v4
	v_mov_b32_e32 v29, v4
	v_mov_b32_e32 v30, v4
	v_mov_b32_e32 v31, v4
	v_mov_b32_e32 v32, v4
	v_mov_b32_e32 v33, v4
	v_mov_b32_e32 v34, v4
	v_mov_b32_e32 v35, v4
	v_mov_b32_e32 v44, v4
	v_mov_b32_e32 v45, v4
	v_mov_b32_e32 v46, v4
	v_mov_b32_e32 v47, v4
	v_mov_b32_e32 v48, v4
	v_mov_b32_e32 v49, v4
	v_mov_b32_e32 v50, v4
	v_mov_b32_e32 v51, v4
	v_mov_b32_e32 v60, v4
	v_mov_b32_e32 v61, v4
	v_mov_b32_e32 v62, v4
	v_mov_b32_e32 v63, v4
	v_mov_b32_e32 v68, v4
	v_mov_b32_e32 v69, v4
	v_mov_b32_e32 v70, v4
	v_mov_b32_e32 v71, v4
	v_mov_b32_e32 v72, v4
	v_mov_b32_e32 v73, v4
	v_mov_b32_e32 v74, v4
	v_mov_b32_e32 v75, v4
	v_mov_b32_e32 v80, v4
	v_mov_b32_e32 v81, v4
	v_mov_b32_e32 v82, v4
	v_mov_b32_e32 v83, v4
	v_mov_b32_e32 v88, v4
	v_mov_b32_e32 v89, v4
	v_mov_b32_e32 v90, v4
	v_mov_b32_e32 v91, v4
	v_mov_b32_e32 v96, v4
	v_mov_b32_e32 v97, v4
	v_mov_b32_e32 v98, v4
	v_mov_b32_e32 v99, v4
	v_mov_b32_e32 v104, v4
	v_mov_b32_e32 v105, v4
	v_mov_b32_e32 v106, v4
	v_mov_b32_e32 v107, v4
	v_mov_b32_e32 v112, v4
	v_mov_b32_e32 v113, v4
	v_mov_b32_e32 v114, v4
	v_mov_b32_e32 v115, v4
	v_mov_b32_e32 v120, v4
	v_mov_b32_e32 v121, v4
	v_mov_b32_e32 v122, v4
	v_mov_b32_e32 v123, v4
	v_mov_b32_e32 v64, v4
	v_mov_b32_e32 v65, v4
	v_mov_b32_e32 v66, v4
	v_mov_b32_e32 v67, v4
	v_mov_b32_e32 v76, v4
	v_mov_b32_e32 v77, v4
	v_mov_b32_e32 v78, v4
	v_mov_b32_e32 v79, v4
	v_mov_b32_e32 v84, v4
	v_mov_b32_e32 v85, v4
	v_mov_b32_e32 v86, v4
	v_mov_b32_e32 v87, v4
	v_mov_b32_e32 v92, v4
	v_mov_b32_e32 v93, v4
	v_mov_b32_e32 v94, v4
	v_mov_b32_e32 v95, v4
	v_mov_b32_e32 v100, v4
	v_mov_b32_e32 v101, v4
	v_mov_b32_e32 v102, v4
	v_mov_b32_e32 v103, v4
	v_mov_b32_e32 v108, v4
	v_mov_b32_e32 v109, v4
	v_mov_b32_e32 v110, v4
	v_mov_b32_e32 v111, v4
	v_mov_b32_e32 v116, v4
	v_mov_b32_e32 v117, v4
	v_mov_b32_e32 v118, v4
	v_mov_b32_e32 v119, v4
	v_mov_b32_e32 v124, v4
	v_mov_b32_e32 v125, v4
	v_mov_b32_e32 v126, v4
	v_mov_b32_e32 v127, v4
	.p2alignl 6, 3212836864

.LBB0_83:
	s_ashr_i32 s37, s36, 31
	s_lshl_b64 s[20:21], s[36:37], 19
	s_add_u32 s92, s24, s20
	s_addc_u32 s93, s25, s21
	s_and_b64 s[20:21], s[40:41], exec
	s_cselect_b32 s9, s93, s15
	s_cselect_b32 s20, s92, s14
	s_ashr_i32 s45, s44, 31
	s_lshl_b64 s[48:49], s[44:45], 19
	s_add_u32 s96, s26, s48
	s_addc_u32 s97, s27, s49
	s_and_b64 s[48:49], s[40:41], exec
	s_cselect_b32 s37, s97, s13
	s_cselect_b32 s45, s96, s12
	s_add_u32 s90, s12, 0x100
	s_addc_u32 s21, s13, 0
	s_add_u32 vcc_lo, s14, 0x40080
	v_mov_b32_e32 v0, 0
	s_addc_u32 vcc_hi, s15, 0
	s_mov_b32 s22, -2
	v_mov_b32_e32 v1, v0
	v_mov_b32_e32 v2, v0
	v_mov_b32_e32 v3, v0
	v_mov_b32_e32 v4, v0
	v_mov_b32_e32 v5, v0
	v_mov_b32_e32 v6, v0
	v_mov_b32_e32 v7, v0
	v_mov_b32_e32 v16, v0
	v_mov_b32_e32 v17, v0
	v_mov_b32_e32 v18, v0
	v_mov_b32_e32 v19, v0
	v_mov_b32_e32 v20, v0
	v_mov_b32_e32 v21, v0
	v_mov_b32_e32 v22, v0
	v_mov_b32_e32 v23, v0
	v_mov_b32_e32 v32, v0
	v_mov_b32_e32 v33, v0
	v_mov_b32_e32 v34, v0
	v_mov_b32_e32 v35, v0
	v_mov_b32_e32 v36, v0
	v_mov_b32_e32 v37, v0
	v_mov_b32_e32 v38, v0
	v_mov_b32_e32 v39, v0
	v_mov_b32_e32 v48, v0
	v_mov_b32_e32 v49, v0
	v_mov_b32_e32 v50, v0
	v_mov_b32_e32 v51, v0
	v_mov_b32_e32 v52, v0
	v_mov_b32_e32 v53, v0
	v_mov_b32_e32 v54, v0
	v_mov_b32_e32 v55, v0
	v_mov_b32_e32 v8, v0
	v_mov_b32_e32 v9, v0
	v_mov_b32_e32 v10, v0
	v_mov_b32_e32 v11, v0
	v_mov_b32_e32 v12, v0
	v_mov_b32_e32 v13, v0
	v_mov_b32_e32 v14, v0
	v_mov_b32_e32 v15, v0
	v_mov_b32_e32 v24, v0
	v_mov_b32_e32 v25, v0
	v_mov_b32_e32 v26, v0
	v_mov_b32_e32 v27, v0
	v_mov_b32_e32 v28, v0
	v_mov_b32_e32 v29, v0
	v_mov_b32_e32 v30, v0
	v_mov_b32_e32 v31, v0
	v_mov_b32_e32 v40, v0
	v_mov_b32_e32 v41, v0
	v_mov_b32_e32 v42, v0
	v_mov_b32_e32 v43, v0
	v_mov_b32_e32 v44, v0
	v_mov_b32_e32 v45, v0
	v_mov_b32_e32 v46, v0
	v_mov_b32_e32 v47, v0
	v_mov_b32_e32 v56, v0
	v_mov_b32_e32 v57, v0
	v_mov_b32_e32 v58, v0
	v_mov_b32_e32 v59, v0
	v_mov_b32_e32 v60, v0
	v_mov_b32_e32 v61, v0
	v_mov_b32_e32 v62, v0
	v_mov_b32_e32 v63, v0
	v_mov_b32_e32 v64, v0
	v_mov_b32_e32 v65, v0
	v_mov_b32_e32 v66, v0
	v_mov_b32_e32 v67, v0
	v_mov_b32_e32 v68, v0
	v_mov_b32_e32 v69, v0
	v_mov_b32_e32 v70, v0
	v_mov_b32_e32 v71, v0
	v_mov_b32_e32 v80, v0
	v_mov_b32_e32 v81, v0
	v_mov_b32_e32 v82, v0
	v_mov_b32_e32 v83, v0
	v_mov_b32_e32 v84, v0
	v_mov_b32_e32 v85, v0
	v_mov_b32_e32 v86, v0
	v_mov_b32_e32 v87, v0
	v_mov_b32_e32 v96, v0
	v_mov_b32_e32 v97, v0
	v_mov_b32_e32 v98, v0
	v_mov_b32_e32 v99, v0
	v_mov_b32_e32 v100, v0
	v_mov_b32_e32 v101, v0
	v_mov_b32_e32 v102, v0
	v_mov_b32_e32 v103, v0
	v_mov_b32_e32 v112, v0
	v_mov_b32_e32 v113, v0
	v_mov_b32_e32 v114, v0
	v_mov_b32_e32 v115, v0
	v_mov_b32_e32 v116, v0
	v_mov_b32_e32 v117, v0
	v_mov_b32_e32 v118, v0
	v_mov_b32_e32 v119, v0
	v_mov_b32_e32 v72, v0
	v_mov_b32_e32 v73, v0
	v_mov_b32_e32 v74, v0
	v_mov_b32_e32 v75, v0
	v_mov_b32_e32 v76, v0
	v_mov_b32_e32 v77, v0
	v_mov_b32_e32 v78, v0
	v_mov_b32_e32 v79, v0
	v_mov_b32_e32 v88, v0
	v_mov_b32_e32 v89, v0
	v_mov_b32_e32 v90, v0
	v_mov_b32_e32 v91, v0
	v_mov_b32_e32 v92, v0
	v_mov_b32_e32 v93, v0
	v_mov_b32_e32 v94, v0
	v_mov_b32_e32 v95, v0
	v_mov_b32_e32 v104, v0
	v_mov_b32_e32 v105, v0
	v_mov_b32_e32 v106, v0
	v_mov_b32_e32 v107, v0
	v_mov_b32_e32 v108, v0
	v_mov_b32_e32 v109, v0
	v_mov_b32_e32 v110, v0
	v_mov_b32_e32 v111, v0
	v_mov_b32_e32 v120, v0
	v_mov_b32_e32 v121, v0
	v_mov_b32_e32 v122, v0
	v_mov_b32_e32 v123, v0
	v_mov_b32_e32 v124, v0
	v_mov_b32_e32 v125, v0
	v_mov_b32_e32 v126, v0
	v_mov_b32_e32 v127, v0
	.p2alignl 6, 3212836864

.LBB0_120:
	s_and_b32 s6, s21, 7
	s_lshl_b32 s6, s6, 8
	s_waitcnt vmcnt(0)
	s_add_i32 s10, s20, 1
	s_or_b32 s6, s8, s6
	s_add_u32 s6, s92, s6
	v_mov_b32_e32 v0, 0
	s_addc_u32 s7, s93, s9
	s_mov_b32 s11, 0
	v_mov_b32_e32 v1, v0
	v_mov_b32_e32 v2, v0
	v_mov_b32_e32 v3, v0
	v_mov_b32_e32 v4, v0
	v_mov_b32_e32 v5, v0
	v_mov_b32_e32 v6, v0
	v_mov_b32_e32 v7, v0
	v_mov_b32_e32 v8, v0
	v_mov_b32_e32 v9, v0
	v_mov_b32_e32 v10, v0
	v_mov_b32_e32 v11, v0
	v_mov_b32_e32 v12, v0
	v_mov_b32_e32 v13, v0
	v_mov_b32_e32 v14, v0
	v_mov_b32_e32 v15, v0
	v_mov_b32_e32 v16, v0
	v_mov_b32_e32 v17, v0
	v_mov_b32_e32 v18, v0
	v_mov_b32_e32 v19, v0
	v_mov_b32_e32 v20, v0
	v_mov_b32_e32 v21, v0
	v_mov_b32_e32 v22, v0
	v_mov_b32_e32 v23, v0
	v_mov_b32_e32 v24, v0
	v_mov_b32_e32 v25, v0
	v_mov_b32_e32 v26, v0
	v_mov_b32_e32 v27, v0
	v_mov_b32_e32 v28, v0
	v_mov_b32_e32 v29, v0
	v_mov_b32_e32 v30, v0
	v_mov_b32_e32 v31, v0
	v_mov_b32_e32 v32, v0
	v_mov_b32_e32 v33, v0
	v_mov_b32_e32 v34, v0
	v_mov_b32_e32 v35, v0
	v_mov_b32_e32 v36, v0
	v_mov_b32_e32 v37, v0
	v_mov_b32_e32 v38, v0
	v_mov_b32_e32 v39, v0
	v_mov_b32_e32 v40, v0
	v_mov_b32_e32 v41, v0
	v_mov_b32_e32 v42, v0
	v_mov_b32_e32 v43, v0
	v_mov_b32_e32 v44, v0
	v_mov_b32_e32 v45, v0
	v_mov_b32_e32 v46, v0
	v_mov_b32_e32 v47, v0
	v_mov_b32_e32 v48, v0
	v_mov_b32_e32 v49, v0
	v_mov_b32_e32 v50, v0
	v_mov_b32_e32 v51, v0
	v_mov_b32_e32 v52, v0
	v_mov_b32_e32 v53, v0
	v_mov_b32_e32 v54, v0
	v_mov_b32_e32 v55, v0
	v_mov_b32_e32 v56, v0
	v_mov_b32_e32 v57, v0
	v_mov_b32_e32 v58, v0
	v_mov_b32_e32 v59, v0
	v_mov_b32_e32 v60, v0
	v_mov_b32_e32 v61, v0
	v_mov_b32_e32 v62, v0
	v_mov_b32_e32 v63, v0
	v_mov_b32_e32 v64, v0
	v_mov_b32_e32 v65, v0
	v_mov_b32_e32 v66, v0
	v_mov_b32_e32 v67, v0
	v_mov_b32_e32 v68, v0
	v_mov_b32_e32 v69, v0
	v_mov_b32_e32 v70, v0
	v_mov_b32_e32 v71, v0
	v_mov_b32_e32 v72, v0
	v_mov_b32_e32 v73, v0
	v_mov_b32_e32 v74, v0
	v_mov_b32_e32 v75, v0
	v_mov_b32_e32 v76, v0
	v_mov_b32_e32 v77, v0
	v_mov_b32_e32 v78, v0
	v_mov_b32_e32 v79, v0
	v_mov_b32_e32 v80, v0
	v_mov_b32_e32 v81, v0
	v_mov_b32_e32 v82, v0
	v_mov_b32_e32 v83, v0
	v_mov_b32_e32 v84, v0
	v_mov_b32_e32 v85, v0
	v_mov_b32_e32 v86, v0
	v_mov_b32_e32 v87, v0
	v_mov_b32_e32 v88, v0
	v_mov_b32_e32 v89, v0
	v_mov_b32_e32 v90, v0
	v_mov_b32_e32 v91, v0
	v_mov_b32_e32 v92, v0
	v_mov_b32_e32 v93, v0
	v_mov_b32_e32 v94, v0
	v_mov_b32_e32 v95, v0
	v_mov_b32_e32 v96, v0
	v_mov_b32_e32 v97, v0
	v_mov_b32_e32 v98, v0
	v_mov_b32_e32 v99, v0
	v_mov_b32_e32 v100, v0
	v_mov_b32_e32 v101, v0
	v_mov_b32_e32 v102, v0
	v_mov_b32_e32 v103, v0
	v_mov_b32_e32 v104, v0
	v_mov_b32_e32 v105, v0
	v_mov_b32_e32 v106, v0
	v_mov_b32_e32 v107, v0
	v_mov_b32_e32 v108, v0
	v_mov_b32_e32 v109, v0
	v_mov_b32_e32 v110, v0
	v_mov_b32_e32 v111, v0
	v_mov_b32_e32 v112, v0
	v_mov_b32_e32 v113, v0
	v_mov_b32_e32 v114, v0
	v_mov_b32_e32 v115, v0
	v_mov_b32_e32 v116, v0
	v_mov_b32_e32 v117, v0
	v_mov_b32_e32 v118, v0
	v_mov_b32_e32 v119, v0
	v_mov_b32_e32 v120, v0
	v_mov_b32_e32 v121, v0
	v_mov_b32_e32 v122, v0
	v_mov_b32_e32 v123, v0
	v_mov_b32_e32 v124, v0
	v_mov_b32_e32 v125, v0
	v_mov_b32_e32 v126, v0
	v_mov_b32_e32 v127, v0
	v_mov_b32_e32 v174, v0
	v_mov_b32_e32 v175, v0
	s_waitcnt lgkmcnt(0)
	s_barrier
	s_branch .LBB0_122
	.p2alignl 6, 3212836864

.LBB0_138:
	s_ashr_i32 s41, s40, 31
	s_lshl_b64 s[12:13], s[40:41], 19
	s_add_u32 s12, s25, s12
	s_addc_u32 s13, s26, s13
	s_and_b64 s[14:15], s[38:39], exec
	s_cselect_b32 s9, s13, s93
	s_cselect_b32 s41, s12, s92
	s_ashr_i32 s45, s44, 31
	s_lshl_b64 s[14:15], s[44:45], 19
	s_add_u32 s96, s27, s14
	s_addc_u32 s97, s28, s15
	s_and_b64 s[14:15], s[38:39], exec
	s_cselect_b32 s45, s97, s11
	s_cselect_b32 vcc_lo, s96, s10
	s_add_u32 vcc_hi, s10, 0x100
	s_addc_u32 s21, s11, 0
	s_add_u32 s10, s92, 0x40080
	v_mov_b32_e32 v0, 0
	s_addc_u32 s11, s93, 0
	s_mov_b32 s22, -2
	v_mov_b32_e32 v1, v0
	v_mov_b32_e32 v2, v0
	v_mov_b32_e32 v3, v0
	v_mov_b32_e32 v4, v0
	v_mov_b32_e32 v5, v0
	v_mov_b32_e32 v6, v0
	v_mov_b32_e32 v7, v0
	v_mov_b32_e32 v16, v0
	v_mov_b32_e32 v17, v0
	v_mov_b32_e32 v18, v0
	v_mov_b32_e32 v19, v0
	v_mov_b32_e32 v20, v0
	v_mov_b32_e32 v21, v0
	v_mov_b32_e32 v22, v0
	v_mov_b32_e32 v23, v0
	v_mov_b32_e32 v32, v0
	v_mov_b32_e32 v33, v0
	v_mov_b32_e32 v34, v0
	v_mov_b32_e32 v35, v0
	v_mov_b32_e32 v36, v0
	v_mov_b32_e32 v37, v0
	v_mov_b32_e32 v38, v0
	v_mov_b32_e32 v39, v0
	v_mov_b32_e32 v48, v0
	v_mov_b32_e32 v49, v0
	v_mov_b32_e32 v50, v0
	v_mov_b32_e32 v51, v0
	v_mov_b32_e32 v52, v0
	v_mov_b32_e32 v53, v0
	v_mov_b32_e32 v54, v0
	v_mov_b32_e32 v55, v0
	v_mov_b32_e32 v8, v0
	v_mov_b32_e32 v9, v0
	v_mov_b32_e32 v10, v0
	v_mov_b32_e32 v11, v0
	v_mov_b32_e32 v12, v0
	v_mov_b32_e32 v13, v0
	v_mov_b32_e32 v14, v0
	v_mov_b32_e32 v15, v0
	v_mov_b32_e32 v24, v0
	v_mov_b32_e32 v25, v0
	v_mov_b32_e32 v26, v0
	v_mov_b32_e32 v27, v0
	v_mov_b32_e32 v28, v0
	v_mov_b32_e32 v29, v0
	v_mov_b32_e32 v30, v0
	v_mov_b32_e32 v31, v0
	v_mov_b32_e32 v40, v0
	v_mov_b32_e32 v41, v0
	v_mov_b32_e32 v42, v0
	v_mov_b32_e32 v43, v0
	v_mov_b32_e32 v44, v0
	v_mov_b32_e32 v45, v0
	v_mov_b32_e32 v46, v0
	v_mov_b32_e32 v47, v0
	v_mov_b32_e32 v56, v0
	v_mov_b32_e32 v57, v0
	v_mov_b32_e32 v58, v0
	v_mov_b32_e32 v59, v0
	v_mov_b32_e32 v60, v0
	v_mov_b32_e32 v61, v0
	v_mov_b32_e32 v62, v0
	v_mov_b32_e32 v63, v0
	v_mov_b32_e32 v64, v0
	v_mov_b32_e32 v65, v0
	v_mov_b32_e32 v66, v0
	v_mov_b32_e32 v67, v0
	v_mov_b32_e32 v68, v0
	v_mov_b32_e32 v69, v0
	v_mov_b32_e32 v70, v0
	v_mov_b32_e32 v71, v0
	v_mov_b32_e32 v80, v0
	v_mov_b32_e32 v81, v0
	v_mov_b32_e32 v82, v0
	v_mov_b32_e32 v83, v0
	v_mov_b32_e32 v84, v0
	v_mov_b32_e32 v85, v0
	v_mov_b32_e32 v86, v0
	v_mov_b32_e32 v87, v0
	v_mov_b32_e32 v96, v0
	v_mov_b32_e32 v97, v0
	v_mov_b32_e32 v98, v0
	v_mov_b32_e32 v99, v0
	v_mov_b32_e32 v100, v0
	v_mov_b32_e32 v101, v0
	v_mov_b32_e32 v102, v0
	v_mov_b32_e32 v103, v0
	v_mov_b32_e32 v112, v0
	v_mov_b32_e32 v113, v0
	v_mov_b32_e32 v114, v0
	v_mov_b32_e32 v115, v0
	v_mov_b32_e32 v116, v0
	v_mov_b32_e32 v117, v0
	v_mov_b32_e32 v118, v0
	v_mov_b32_e32 v119, v0
	v_mov_b32_e32 v72, v0
	v_mov_b32_e32 v73, v0
	v_mov_b32_e32 v74, v0
	v_mov_b32_e32 v75, v0
	v_mov_b32_e32 v76, v0
	v_mov_b32_e32 v77, v0
	v_mov_b32_e32 v78, v0
	v_mov_b32_e32 v79, v0
	v_mov_b32_e32 v88, v0
	v_mov_b32_e32 v89, v0
	v_mov_b32_e32 v90, v0
	v_mov_b32_e32 v91, v0
	v_mov_b32_e32 v92, v0
	v_mov_b32_e32 v93, v0
	v_mov_b32_e32 v94, v0
	v_mov_b32_e32 v95, v0
	v_mov_b32_e32 v104, v0
	v_mov_b32_e32 v105, v0
	v_mov_b32_e32 v106, v0
	v_mov_b32_e32 v107, v0
	v_mov_b32_e32 v108, v0
	v_mov_b32_e32 v109, v0
	v_mov_b32_e32 v110, v0
	v_mov_b32_e32 v111, v0
	v_mov_b32_e32 v120, v0
	v_mov_b32_e32 v121, v0
	v_mov_b32_e32 v122, v0
	v_mov_b32_e32 v123, v0
	v_mov_b32_e32 v124, v0
	v_mov_b32_e32 v125, v0
	v_mov_b32_e32 v126, v0
	v_mov_b32_e32 v127, v0
	.p2alignl 6, 3212836864

.LBB0_177:
	s_add_u32 s21, s10, 0x100
	v_mov_b32_e32 v0, 0
	s_addc_u32 s96, s11, 0
	s_mov_b32 s22, -2
	v_mov_b32_e32 v1, v0
	v_mov_b32_e32 v2, v0
	v_mov_b32_e32 v3, v0
	v_mov_b32_e32 v4, v0
	v_mov_b32_e32 v5, v0
	v_mov_b32_e32 v6, v0
	v_mov_b32_e32 v7, v0
	v_mov_b32_e32 v16, v0
	v_mov_b32_e32 v17, v0
	v_mov_b32_e32 v18, v0
	v_mov_b32_e32 v19, v0
	v_mov_b32_e32 v20, v0
	v_mov_b32_e32 v21, v0
	v_mov_b32_e32 v22, v0
	v_mov_b32_e32 v23, v0
	v_mov_b32_e32 v32, v0
	v_mov_b32_e32 v33, v0
	v_mov_b32_e32 v34, v0
	v_mov_b32_e32 v35, v0
	v_mov_b32_e32 v36, v0
	v_mov_b32_e32 v37, v0
	v_mov_b32_e32 v38, v0
	v_mov_b32_e32 v39, v0
	v_mov_b32_e32 v48, v0
	v_mov_b32_e32 v49, v0
	v_mov_b32_e32 v50, v0
	v_mov_b32_e32 v51, v0
	v_mov_b32_e32 v52, v0
	v_mov_b32_e32 v53, v0
	v_mov_b32_e32 v54, v0
	v_mov_b32_e32 v55, v0
	v_mov_b32_e32 v8, v0
	v_mov_b32_e32 v9, v0
	v_mov_b32_e32 v10, v0
	v_mov_b32_e32 v11, v0
	v_mov_b32_e32 v12, v0
	v_mov_b32_e32 v13, v0
	v_mov_b32_e32 v14, v0
	v_mov_b32_e32 v15, v0
	v_mov_b32_e32 v24, v0
	v_mov_b32_e32 v25, v0
	v_mov_b32_e32 v26, v0
	v_mov_b32_e32 v27, v0
	v_mov_b32_e32 v28, v0
	v_mov_b32_e32 v29, v0
	v_mov_b32_e32 v30, v0
	v_mov_b32_e32 v31, v0
	v_mov_b32_e32 v40, v0
	v_mov_b32_e32 v41, v0
	v_mov_b32_e32 v42, v0
	v_mov_b32_e32 v43, v0
	v_mov_b32_e32 v44, v0
	v_mov_b32_e32 v45, v0
	v_mov_b32_e32 v46, v0
	v_mov_b32_e32 v47, v0
	v_mov_b32_e32 v56, v0
	v_mov_b32_e32 v57, v0
	v_mov_b32_e32 v58, v0
	v_mov_b32_e32 v59, v0
	v_mov_b32_e32 v60, v0
	v_mov_b32_e32 v61, v0
	v_mov_b32_e32 v62, v0
	v_mov_b32_e32 v63, v0
	v_mov_b32_e32 v64, v0
	v_mov_b32_e32 v65, v0
	v_mov_b32_e32 v66, v0
	v_mov_b32_e32 v67, v0
	v_mov_b32_e32 v68, v0
	v_mov_b32_e32 v69, v0
	v_mov_b32_e32 v70, v0
	v_mov_b32_e32 v71, v0
	v_mov_b32_e32 v80, v0
	v_mov_b32_e32 v81, v0
	v_mov_b32_e32 v82, v0
	v_mov_b32_e32 v83, v0
	v_mov_b32_e32 v84, v0
	v_mov_b32_e32 v85, v0
	v_mov_b32_e32 v86, v0
	v_mov_b32_e32 v87, v0
	v_mov_b32_e32 v96, v0
	v_mov_b32_e32 v97, v0
	v_mov_b32_e32 v98, v0
	v_mov_b32_e32 v99, v0
	v_mov_b32_e32 v100, v0
	v_mov_b32_e32 v101, v0
	v_mov_b32_e32 v102, v0
	v_mov_b32_e32 v103, v0
	v_mov_b32_e32 v112, v0
	v_mov_b32_e32 v113, v0
	v_mov_b32_e32 v114, v0
	v_mov_b32_e32 v115, v0
	v_mov_b32_e32 v116, v0
	v_mov_b32_e32 v117, v0
	v_mov_b32_e32 v118, v0
	v_mov_b32_e32 v119, v0
	v_mov_b32_e32 v72, v0
	v_mov_b32_e32 v73, v0
	v_mov_b32_e32 v74, v0
	v_mov_b32_e32 v75, v0
	v_mov_b32_e32 v76, v0
	v_mov_b32_e32 v77, v0
	v_mov_b32_e32 v78, v0
	v_mov_b32_e32 v79, v0
	v_mov_b32_e32 v88, v0
	v_mov_b32_e32 v89, v0
	v_mov_b32_e32 v90, v0
	v_mov_b32_e32 v91, v0
	v_mov_b32_e32 v92, v0
	v_mov_b32_e32 v93, v0
	v_mov_b32_e32 v94, v0
	v_mov_b32_e32 v95, v0
	v_mov_b32_e32 v104, v0
	v_mov_b32_e32 v105, v0
	v_mov_b32_e32 v106, v0
	v_mov_b32_e32 v107, v0
	v_mov_b32_e32 v108, v0
	v_mov_b32_e32 v109, v0
	v_mov_b32_e32 v110, v0
	v_mov_b32_e32 v111, v0
	v_mov_b32_e32 v120, v0
	v_mov_b32_e32 v121, v0
	v_mov_b32_e32 v122, v0
	v_mov_b32_e32 v123, v0
	v_mov_b32_e32 v124, v0
	v_mov_b32_e32 v125, v0
	v_mov_b32_e32 v126, v0
	v_mov_b32_e32 v127, v0
	.p2alignl 6, 3212836864

.LBB0_211:
	s_ashr_i32 s37, s36, 31
	s_lshl_b64 s[14:15], s[36:37], 19
	s_add_u32 s44, s24, s14
	s_addc_u32 s45, s25, s15
	s_and_b64 s[14:15], s[38:39], exec
	s_cselect_b32 s20, s45, s13
	s_cselect_b32 s37, s44, s12
	s_ashr_i32 s41, s40, 31
	s_lshl_b64 s[14:15], s[40:41], 19
	s_add_u32 s92, s26, s14
	s_addc_u32 s93, s27, s15
	s_and_b64 s[14:15], s[38:39], exec
	s_cselect_b32 s41, s93, s11
	s_cselect_b32 s91, s92, s10
	s_add_u32 s96, s10, 0x100
	s_addc_u32 s97, s11, 0
	s_add_u32 s10, s12, 0x40080
	v_mov_b32_e32 v4, 0
	s_addc_u32 s11, s13, 0
	s_mov_b32 s21, -2
	v_mov_b32_e32 v5, v4
	v_mov_b32_e32 v6, v4
	v_mov_b32_e32 v7, v4
	v_mov_b32_e32 v8, v4
	v_mov_b32_e32 v9, v4
	v_mov_b32_e32 v10, v4
	v_mov_b32_e32 v11, v4
	v_mov_b32_e32 v20, v4
	v_mov_b32_e32 v21, v4
	v_mov_b32_e32 v22, v4
	v_mov_b32_e32 v23, v4
	v_mov_b32_e32 v24, v4
	v_mov_b32_e32 v25, v4
	v_mov_b32_e32 v26, v4
	v_mov_b32_e32 v27, v4
	v_mov_b32_e32 v36, v4
	v_mov_b32_e32 v37, v4
	v_mov_b32_e32 v38, v4
	v_mov_b32_e32 v39, v4
	v_mov_b32_e32 v40, v4
	v_mov_b32_e32 v41, v4
	v_mov_b32_e32 v42, v4
	v_mov_b32_e32 v43, v4
	v_mov_b32_e32 v52, v4
	v_mov_b32_e32 v53, v4
	v_mov_b32_e32 v54, v4
	v_mov_b32_e32 v55, v4
	v_mov_b32_e32 v56, v4
	v_mov_b32_e32 v57, v4
	v_mov_b32_e32 v58, v4
	v_mov_b32_e32 v59, v4
	v_mov_b32_e32 v0, v4
	v_mov_b32_e32 v1, v4
	v_mov_b32_e32 v2, v4
	v_mov_b32_e32 v3, v4
	v_mov_b32_e32 v12, v4
	v_mov_b32_e32 v13, v4
	v_mov_b32_e32 v14, v4
	v_mov_b32_e32 v15, v4
	v_mov_b32_e32 v16, v4
	v_mov_b32_e32 v17, v4
	v_mov_b32_e32 v18, v4
	v_mov_b32_e32 v19, v4
	v_mov_b32_e32 v28, v4
	v_mov_b32_e32 v29, v4
	v_mov_b32_e32 v30, v4
	v_mov_b32_e32 v31, v4
	v_mov_b32_e32 v32, v4
	v_mov_b32_e32 v33, v4
	v_mov_b32_e32 v34, v4
	v_mov_b32_e32 v35, v4
	v_mov_b32_e32 v44, v4
	v_mov_b32_e32 v45, v4
	v_mov_b32_e32 v46, v4
	v_mov_b32_e32 v47, v4
	v_mov_b32_e32 v48, v4
	v_mov_b32_e32 v49, v4
	v_mov_b32_e32 v50, v4
	v_mov_b32_e32 v51, v4
	v_mov_b32_e32 v60, v4
	v_mov_b32_e32 v61, v4
	v_mov_b32_e32 v62, v4
	v_mov_b32_e32 v63, v4
	v_mov_b32_e32 v68, v4
	v_mov_b32_e32 v69, v4
	v_mov_b32_e32 v70, v4
	v_mov_b32_e32 v71, v4
	v_mov_b32_e32 v72, v4
	v_mov_b32_e32 v73, v4
	v_mov_b32_e32 v74, v4
	v_mov_b32_e32 v75, v4
	v_mov_b32_e32 v80, v4
	v_mov_b32_e32 v81, v4
	v_mov_b32_e32 v82, v4
	v_mov_b32_e32 v83, v4
	v_mov_b32_e32 v88, v4
	v_mov_b32_e32 v89, v4
	v_mov_b32_e32 v90, v4
	v_mov_b32_e32 v91, v4
	v_mov_b32_e32 v96, v4
	v_mov_b32_e32 v97, v4
	v_mov_b32_e32 v98, v4
	v_mov_b32_e32 v99, v4
	v_mov_b32_e32 v104, v4
	v_mov_b32_e32 v105, v4
	v_mov_b32_e32 v106, v4
	v_mov_b32_e32 v107, v4
	v_mov_b32_e32 v112, v4
	v_mov_b32_e32 v113, v4
	v_mov_b32_e32 v114, v4
	v_mov_b32_e32 v115, v4
	v_mov_b32_e32 v120, v4
	v_mov_b32_e32 v121, v4
	v_mov_b32_e32 v122, v4
	v_mov_b32_e32 v123, v4
	v_mov_b32_e32 v64, v4
	v_mov_b32_e32 v65, v4
	v_mov_b32_e32 v66, v4
	v_mov_b32_e32 v67, v4
	v_mov_b32_e32 v76, v4
	v_mov_b32_e32 v77, v4
	v_mov_b32_e32 v78, v4
	v_mov_b32_e32 v79, v4
	v_mov_b32_e32 v84, v4
	v_mov_b32_e32 v85, v4
	v_mov_b32_e32 v86, v4
	v_mov_b32_e32 v87, v4
	v_mov_b32_e32 v92, v4
	v_mov_b32_e32 v93, v4
	v_mov_b32_e32 v94, v4
	v_mov_b32_e32 v95, v4
	v_mov_b32_e32 v100, v4
	v_mov_b32_e32 v101, v4
	v_mov_b32_e32 v102, v4
	v_mov_b32_e32 v103, v4
	v_mov_b32_e32 v108, v4
	v_mov_b32_e32 v109, v4
	v_mov_b32_e32 v110, v4
	v_mov_b32_e32 v111, v4
	v_mov_b32_e32 v116, v4
	v_mov_b32_e32 v117, v4
	v_mov_b32_e32 v118, v4
	v_mov_b32_e32 v119, v4
	v_mov_b32_e32 v124, v4
	v_mov_b32_e32 v125, v4
	v_mov_b32_e32 v126, v4
	v_mov_b32_e32 v127, v4
	.p2alignl 6, 3212836864

.LBB0_309:
	s_ashr_i32 s9, s8, 31
	s_lshl_b64 s[14:15], s[8:9], 19
	s_add_u32 s14, s24, s14
	s_addc_u32 s15, s25, s15
	s_and_b64 s[20:21], s[40:41], exec
	s_cselect_b32 s9, s15, s93
	s_cselect_b32 s20, s14, s92
	s_ashr_i32 s11, s10, 31
	s_lshl_b64 s[90:91], s[10:11], 19
	s_add_u32 s96, s26, s90
	s_addc_u32 s97, s27, s91
	s_and_b64 s[90:91], s[40:41], exec
	s_cselect_b32 s11, s97, s13
	s_cselect_b32 s45, s96, s12
	s_add_u32 s90, s12, 0x100
	s_addc_u32 s91, s13, 0
	s_add_u32 vcc_lo, s92, 0x40080
	v_mov_b32_e32 v0, 0
	s_addc_u32 vcc_hi, s93, 0
	s_mov_b32 s21, -2
	v_mov_b32_e32 v1, v0
	v_mov_b32_e32 v2, v0
	v_mov_b32_e32 v3, v0
	v_mov_b32_e32 v4, v0
	v_mov_b32_e32 v5, v0
	v_mov_b32_e32 v6, v0
	v_mov_b32_e32 v7, v0
	v_mov_b32_e32 v16, v0
	v_mov_b32_e32 v17, v0
	v_mov_b32_e32 v18, v0
	v_mov_b32_e32 v19, v0
	v_mov_b32_e32 v20, v0
	v_mov_b32_e32 v21, v0
	v_mov_b32_e32 v22, v0
	v_mov_b32_e32 v23, v0
	v_mov_b32_e32 v32, v0
	v_mov_b32_e32 v33, v0
	v_mov_b32_e32 v34, v0
	v_mov_b32_e32 v35, v0
	v_mov_b32_e32 v36, v0
	v_mov_b32_e32 v37, v0
	v_mov_b32_e32 v38, v0
	v_mov_b32_e32 v39, v0
	v_mov_b32_e32 v48, v0
	v_mov_b32_e32 v49, v0
	v_mov_b32_e32 v50, v0
	v_mov_b32_e32 v51, v0
	v_mov_b32_e32 v52, v0
	v_mov_b32_e32 v53, v0
	v_mov_b32_e32 v54, v0
	v_mov_b32_e32 v55, v0
	v_mov_b32_e32 v8, v0
	v_mov_b32_e32 v9, v0
	v_mov_b32_e32 v10, v0
	v_mov_b32_e32 v11, v0
	v_mov_b32_e32 v12, v0
	v_mov_b32_e32 v13, v0
	v_mov_b32_e32 v14, v0
	v_mov_b32_e32 v15, v0
	v_mov_b32_e32 v24, v0
	v_mov_b32_e32 v25, v0
	v_mov_b32_e32 v26, v0
	v_mov_b32_e32 v27, v0
	v_mov_b32_e32 v28, v0
	v_mov_b32_e32 v29, v0
	v_mov_b32_e32 v30, v0
	v_mov_b32_e32 v31, v0
	v_mov_b32_e32 v40, v0
	v_mov_b32_e32 v41, v0
	v_mov_b32_e32 v42, v0
	v_mov_b32_e32 v43, v0
	v_mov_b32_e32 v44, v0
	v_mov_b32_e32 v45, v0
	v_mov_b32_e32 v46, v0
	v_mov_b32_e32 v47, v0
	v_mov_b32_e32 v56, v0
	v_mov_b32_e32 v57, v0
	v_mov_b32_e32 v58, v0
	v_mov_b32_e32 v59, v0
	v_mov_b32_e32 v60, v0
	v_mov_b32_e32 v61, v0
	v_mov_b32_e32 v62, v0
	v_mov_b32_e32 v63, v0
	v_mov_b32_e32 v64, v0
	v_mov_b32_e32 v65, v0
	v_mov_b32_e32 v66, v0
	v_mov_b32_e32 v67, v0
	v_mov_b32_e32 v68, v0
	v_mov_b32_e32 v69, v0
	v_mov_b32_e32 v70, v0
	v_mov_b32_e32 v71, v0
	v_mov_b32_e32 v80, v0
	v_mov_b32_e32 v81, v0
	v_mov_b32_e32 v82, v0
	v_mov_b32_e32 v83, v0
	v_mov_b32_e32 v84, v0
	v_mov_b32_e32 v85, v0
	v_mov_b32_e32 v86, v0
	v_mov_b32_e32 v87, v0
	v_mov_b32_e32 v96, v0
	v_mov_b32_e32 v97, v0
	v_mov_b32_e32 v98, v0
	v_mov_b32_e32 v99, v0
	v_mov_b32_e32 v100, v0
	v_mov_b32_e32 v101, v0
	v_mov_b32_e32 v102, v0
	v_mov_b32_e32 v103, v0
	v_mov_b32_e32 v112, v0
	v_mov_b32_e32 v113, v0
	v_mov_b32_e32 v114, v0
	v_mov_b32_e32 v115, v0
	v_mov_b32_e32 v116, v0
	v_mov_b32_e32 v117, v0
	v_mov_b32_e32 v118, v0
	v_mov_b32_e32 v119, v0
	v_mov_b32_e32 v72, v0
	v_mov_b32_e32 v73, v0
	v_mov_b32_e32 v74, v0
	v_mov_b32_e32 v75, v0
	v_mov_b32_e32 v76, v0
	v_mov_b32_e32 v77, v0
	v_mov_b32_e32 v78, v0
	v_mov_b32_e32 v79, v0
	v_mov_b32_e32 v88, v0
	v_mov_b32_e32 v89, v0
	v_mov_b32_e32 v90, v0
	v_mov_b32_e32 v91, v0
	v_mov_b32_e32 v92, v0
	v_mov_b32_e32 v93, v0
	v_mov_b32_e32 v94, v0
	v_mov_b32_e32 v95, v0
	v_mov_b32_e32 v104, v0
	v_mov_b32_e32 v105, v0
	v_mov_b32_e32 v106, v0
	v_mov_b32_e32 v107, v0
	v_mov_b32_e32 v108, v0
	v_mov_b32_e32 v109, v0
	v_mov_b32_e32 v110, v0
	v_mov_b32_e32 v111, v0
	v_mov_b32_e32 v120, v0
	v_mov_b32_e32 v121, v0
	v_mov_b32_e32 v122, v0
	v_mov_b32_e32 v123, v0
	v_mov_b32_e32 v124, v0
	v_mov_b32_e32 v125, v0
	v_mov_b32_e32 v126, v0
	v_mov_b32_e32 v127, v0
	.p2alignl 6, 3212836864

.LBB0_398:
	s_ashr_i32 s7, s6, 31
	s_lshl_b64 s[2:3], s[6:7], 19
	s_add_u32 s2, s13, s2
	s_addc_u32 s3, s14, s3
	s_and_b64 s[4:5], s[38:39], exec
	s_cselect_b32 s7, s3, s9
	s_cselect_b32 s19, s2, s8
	s_ashr_i32 s97, s96, 31
	s_lshl_b64 s[4:5], s[96:97], 19
	s_add_u32 s4, s15, s4
	s_addc_u32 s5, s24, s5
	s_and_b64 s[10:11], s[38:39], exec
	s_cselect_b32 s20, s5, s1
	s_cselect_b32 s33, s4, s0
	s_add_u32 s90, s0, 0x100
	s_addc_u32 s91, s1, 0
	s_add_u32 s0, s8, 0x40080
	v_mov_b32_e32 v0, 0
	s_addc_u32 s1, s9, 0
	s_mov_b32 s21, -2
	v_mov_b32_e32 v1, v0
	v_mov_b32_e32 v2, v0
	v_mov_b32_e32 v3, v0
	v_mov_b32_e32 v8, v0
	v_mov_b32_e32 v9, v0
	v_mov_b32_e32 v10, v0
	v_mov_b32_e32 v11, v0
	v_mov_b32_e32 v16, v0
	v_mov_b32_e32 v17, v0
	v_mov_b32_e32 v18, v0
	v_mov_b32_e32 v19, v0
	v_mov_b32_e32 v24, v0
	v_mov_b32_e32 v25, v0
	v_mov_b32_e32 v26, v0
	v_mov_b32_e32 v27, v0
	v_mov_b32_e32 v32, v0
	v_mov_b32_e32 v33, v0
	v_mov_b32_e32 v34, v0
	v_mov_b32_e32 v35, v0
	v_mov_b32_e32 v40, v0
	v_mov_b32_e32 v41, v0
	v_mov_b32_e32 v42, v0
	v_mov_b32_e32 v43, v0
	v_mov_b32_e32 v48, v0
	v_mov_b32_e32 v49, v0
	v_mov_b32_e32 v50, v0
	v_mov_b32_e32 v51, v0
	v_mov_b32_e32 v56, v0
	v_mov_b32_e32 v57, v0
	v_mov_b32_e32 v58, v0
	v_mov_b32_e32 v59, v0
	v_mov_b32_e32 v4, v0
	v_mov_b32_e32 v5, v0
	v_mov_b32_e32 v6, v0
	v_mov_b32_e32 v7, v0
	v_mov_b32_e32 v12, v0
	v_mov_b32_e32 v13, v0
	v_mov_b32_e32 v14, v0
	v_mov_b32_e32 v15, v0
	v_mov_b32_e32 v20, v0
	v_mov_b32_e32 v21, v0
	v_mov_b32_e32 v22, v0
	v_mov_b32_e32 v23, v0
	v_mov_b32_e32 v28, v0
	v_mov_b32_e32 v29, v0
	v_mov_b32_e32 v30, v0
	v_mov_b32_e32 v31, v0
	v_mov_b32_e32 v36, v0
	v_mov_b32_e32 v37, v0
	v_mov_b32_e32 v38, v0
	v_mov_b32_e32 v39, v0
	v_mov_b32_e32 v44, v0
	v_mov_b32_e32 v45, v0
	v_mov_b32_e32 v46, v0
	v_mov_b32_e32 v47, v0
	v_mov_b32_e32 v52, v0
	v_mov_b32_e32 v53, v0
	v_mov_b32_e32 v54, v0
	v_mov_b32_e32 v55, v0
	v_mov_b32_e32 v60, v0
	v_mov_b32_e32 v61, v0
	v_mov_b32_e32 v62, v0
	v_mov_b32_e32 v63, v0
	v_mov_b32_e32 v64, v0
	v_mov_b32_e32 v65, v0
	v_mov_b32_e32 v66, v0
	v_mov_b32_e32 v67, v0
	v_mov_b32_e32 v72, v0
	v_mov_b32_e32 v73, v0
	v_mov_b32_e32 v74, v0
	v_mov_b32_e32 v75, v0
	v_mov_b32_e32 v80, v0
	v_mov_b32_e32 v81, v0
	v_mov_b32_e32 v82, v0
	v_mov_b32_e32 v83, v0
	v_mov_b32_e32 v88, v0
	v_mov_b32_e32 v89, v0
	v_mov_b32_e32 v90, v0
	v_mov_b32_e32 v91, v0
	v_mov_b32_e32 v96, v0
	v_mov_b32_e32 v97, v0
	v_mov_b32_e32 v98, v0
	v_mov_b32_e32 v99, v0
	v_mov_b32_e32 v104, v0
	v_mov_b32_e32 v105, v0
	v_mov_b32_e32 v106, v0
	v_mov_b32_e32 v107, v0
	v_mov_b32_e32 v112, v0
	v_mov_b32_e32 v113, v0
	v_mov_b32_e32 v114, v0
	v_mov_b32_e32 v115, v0
	v_mov_b32_e32 v120, v0
	v_mov_b32_e32 v121, v0
	v_mov_b32_e32 v122, v0
	v_mov_b32_e32 v123, v0
	v_mov_b32_e32 v68, v0
	v_mov_b32_e32 v69, v0
	v_mov_b32_e32 v70, v0
	v_mov_b32_e32 v71, v0
	v_mov_b32_e32 v76, v0
	v_mov_b32_e32 v77, v0
	v_mov_b32_e32 v78, v0
	v_mov_b32_e32 v79, v0
	v_mov_b32_e32 v84, v0
	v_mov_b32_e32 v85, v0
	v_mov_b32_e32 v86, v0
	v_mov_b32_e32 v87, v0
	v_mov_b32_e32 v92, v0
	v_mov_b32_e32 v93, v0
	v_mov_b32_e32 v94, v0
	v_mov_b32_e32 v95, v0
	v_mov_b32_e32 v100, v0
	v_mov_b32_e32 v101, v0
	v_mov_b32_e32 v102, v0
	v_mov_b32_e32 v103, v0
	v_mov_b32_e32 v108, v0
	v_mov_b32_e32 v109, v0
	v_mov_b32_e32 v110, v0
	v_mov_b32_e32 v111, v0
	v_mov_b32_e32 v116, v0
	v_mov_b32_e32 v117, v0
	v_mov_b32_e32 v118, v0
	v_mov_b32_e32 v119, v0
	v_mov_b32_e32 v124, v0
	v_mov_b32_e32 v125, v0
	v_mov_b32_e32 v126, v0
	v_mov_b32_e32 v127, v0
	.p2alignl 6, 3212836864

.LBB0_438:
	s_add_u32 s21, s10, 0x100
	v_mov_b32_e32 v0, 0
	s_addc_u32 s92, s11, 0
	s_mov_b32 s22, -2
	v_mov_b32_e32 v1, v0
	v_mov_b32_e32 v2, v0
	v_mov_b32_e32 v3, v0
	v_mov_b32_e32 v4, v0
	v_mov_b32_e32 v5, v0
	v_mov_b32_e32 v6, v0
	v_mov_b32_e32 v7, v0
	v_mov_b32_e32 v16, v0
	v_mov_b32_e32 v17, v0
	v_mov_b32_e32 v18, v0
	v_mov_b32_e32 v19, v0
	v_mov_b32_e32 v20, v0
	v_mov_b32_e32 v21, v0
	v_mov_b32_e32 v22, v0
	v_mov_b32_e32 v23, v0
	v_mov_b32_e32 v32, v0
	v_mov_b32_e32 v33, v0
	v_mov_b32_e32 v34, v0
	v_mov_b32_e32 v35, v0
	v_mov_b32_e32 v36, v0
	v_mov_b32_e32 v37, v0
	v_mov_b32_e32 v38, v0
	v_mov_b32_e32 v39, v0
	v_mov_b32_e32 v48, v0
	v_mov_b32_e32 v49, v0
	v_mov_b32_e32 v50, v0
	v_mov_b32_e32 v51, v0
	v_mov_b32_e32 v52, v0
	v_mov_b32_e32 v53, v0
	v_mov_b32_e32 v54, v0
	v_mov_b32_e32 v55, v0
	v_mov_b32_e32 v8, v0
	v_mov_b32_e32 v9, v0
	v_mov_b32_e32 v10, v0
	v_mov_b32_e32 v11, v0
	v_mov_b32_e32 v12, v0
	v_mov_b32_e32 v13, v0
	v_mov_b32_e32 v14, v0
	v_mov_b32_e32 v15, v0
	v_mov_b32_e32 v24, v0
	v_mov_b32_e32 v25, v0
	v_mov_b32_e32 v26, v0
	v_mov_b32_e32 v27, v0
	v_mov_b32_e32 v28, v0
	v_mov_b32_e32 v29, v0
	v_mov_b32_e32 v30, v0
	v_mov_b32_e32 v31, v0
	v_mov_b32_e32 v40, v0
	v_mov_b32_e32 v41, v0
	v_mov_b32_e32 v42, v0
	v_mov_b32_e32 v43, v0
	v_mov_b32_e32 v44, v0
	v_mov_b32_e32 v45, v0
	v_mov_b32_e32 v46, v0
	v_mov_b32_e32 v47, v0
	v_mov_b32_e32 v56, v0
	v_mov_b32_e32 v57, v0
	v_mov_b32_e32 v58, v0
	v_mov_b32_e32 v59, v0
	v_mov_b32_e32 v60, v0
	v_mov_b32_e32 v61, v0
	v_mov_b32_e32 v62, v0
	v_mov_b32_e32 v63, v0
	v_mov_b32_e32 v64, v0
	v_mov_b32_e32 v65, v0
	v_mov_b32_e32 v66, v0
	v_mov_b32_e32 v67, v0
	v_mov_b32_e32 v68, v0
	v_mov_b32_e32 v69, v0
	v_mov_b32_e32 v70, v0
	v_mov_b32_e32 v71, v0
	v_mov_b32_e32 v80, v0
	v_mov_b32_e32 v81, v0
	v_mov_b32_e32 v82, v0
	v_mov_b32_e32 v83, v0
	v_mov_b32_e32 v84, v0
	v_mov_b32_e32 v85, v0
	v_mov_b32_e32 v86, v0
	v_mov_b32_e32 v87, v0
	v_mov_b32_e32 v96, v0
	v_mov_b32_e32 v97, v0
	v_mov_b32_e32 v98, v0
	v_mov_b32_e32 v99, v0
	v_mov_b32_e32 v100, v0
	v_mov_b32_e32 v101, v0
	v_mov_b32_e32 v102, v0
	v_mov_b32_e32 v103, v0
	v_mov_b32_e32 v112, v0
	v_mov_b32_e32 v113, v0
	v_mov_b32_e32 v114, v0
	v_mov_b32_e32 v115, v0
	v_mov_b32_e32 v116, v0
	v_mov_b32_e32 v117, v0
	v_mov_b32_e32 v118, v0
	v_mov_b32_e32 v119, v0
	v_mov_b32_e32 v72, v0
	v_mov_b32_e32 v73, v0
	v_mov_b32_e32 v74, v0
	v_mov_b32_e32 v75, v0
	v_mov_b32_e32 v76, v0
	v_mov_b32_e32 v77, v0
	v_mov_b32_e32 v78, v0
	v_mov_b32_e32 v79, v0
	v_mov_b32_e32 v88, v0
	v_mov_b32_e32 v89, v0
	v_mov_b32_e32 v90, v0
	v_mov_b32_e32 v91, v0
	v_mov_b32_e32 v92, v0
	v_mov_b32_e32 v93, v0
	v_mov_b32_e32 v94, v0
	v_mov_b32_e32 v95, v0
	v_mov_b32_e32 v104, v0
	v_mov_b32_e32 v105, v0
	v_mov_b32_e32 v106, v0
	v_mov_b32_e32 v107, v0
	v_mov_b32_e32 v108, v0
	v_mov_b32_e32 v109, v0
	v_mov_b32_e32 v110, v0
	v_mov_b32_e32 v111, v0
	v_mov_b32_e32 v120, v0
	v_mov_b32_e32 v121, v0
	v_mov_b32_e32 v122, v0
	v_mov_b32_e32 v123, v0
	v_mov_b32_e32 v124, v0
	v_mov_b32_e32 v125, v0
	v_mov_b32_e32 v126, v0
	v_mov_b32_e32 v127, v0
	.p2alignl 6, 3212836864

.LBB0_473:
	s_ashr_i32 s37, s36, 31
	s_lshl_b64 s[14:15], s[36:37], 19
	s_add_u32 s44, s24, s14
	s_addc_u32 s45, s25, s15
	s_and_b64 s[14:15], s[38:39], exec
	s_cselect_b32 s20, s45, s13
	s_cselect_b32 s37, s44, s12
	s_ashr_i32 s41, s40, 31
	s_lshl_b64 s[14:15], s[40:41], 19
	s_add_u32 s46, s26, s14
	s_addc_u32 s47, s27, s15
	s_and_b64 s[14:15], s[38:39], exec
	s_cselect_b32 s41, s47, s11
	s_cselect_b32 s91, s46, s10
	s_add_u32 s92, s10, 0x100
	s_addc_u32 s93, s11, 0
	s_add_u32 s10, s12, 0x40080
	v_mov_b32_e32 v4, 0
	s_addc_u32 s11, s13, 0
	s_mov_b32 s21, -2
	v_mov_b32_e32 v5, v4
	v_mov_b32_e32 v6, v4
	v_mov_b32_e32 v7, v4
	v_mov_b32_e32 v8, v4
	v_mov_b32_e32 v9, v4
	v_mov_b32_e32 v10, v4
	v_mov_b32_e32 v11, v4
	v_mov_b32_e32 v20, v4
	v_mov_b32_e32 v21, v4
	v_mov_b32_e32 v22, v4
	v_mov_b32_e32 v23, v4
	v_mov_b32_e32 v24, v4
	v_mov_b32_e32 v25, v4
	v_mov_b32_e32 v26, v4
	v_mov_b32_e32 v27, v4
	v_mov_b32_e32 v36, v4
	v_mov_b32_e32 v37, v4
	v_mov_b32_e32 v38, v4
	v_mov_b32_e32 v39, v4
	v_mov_b32_e32 v40, v4
	v_mov_b32_e32 v41, v4
	v_mov_b32_e32 v42, v4
	v_mov_b32_e32 v43, v4
	v_mov_b32_e32 v52, v4
	v_mov_b32_e32 v53, v4
	v_mov_b32_e32 v54, v4
	v_mov_b32_e32 v55, v4
	v_mov_b32_e32 v56, v4
	v_mov_b32_e32 v57, v4
	v_mov_b32_e32 v58, v4
	v_mov_b32_e32 v59, v4
	v_mov_b32_e32 v0, v4
	v_mov_b32_e32 v1, v4
	v_mov_b32_e32 v2, v4
	v_mov_b32_e32 v3, v4
	v_mov_b32_e32 v12, v4
	v_mov_b32_e32 v13, v4
	v_mov_b32_e32 v14, v4
	v_mov_b32_e32 v15, v4
	v_mov_b32_e32 v16, v4
	v_mov_b32_e32 v17, v4
	v_mov_b32_e32 v18, v4
	v_mov_b32_e32 v19, v4
	v_mov_b32_e32 v28, v4
	v_mov_b32_e32 v29, v4
	v_mov_b32_e32 v30, v4
	v_mov_b32_e32 v31, v4
	v_mov_b32_e32 v32, v4
	v_mov_b32_e32 v33, v4
	v_mov_b32_e32 v34, v4
	v_mov_b32_e32 v35, v4
	v_mov_b32_e32 v44, v4
	v_mov_b32_e32 v45, v4
	v_mov_b32_e32 v46, v4
	v_mov_b32_e32 v47, v4
	v_mov_b32_e32 v48, v4
	v_mov_b32_e32 v49, v4
	v_mov_b32_e32 v50, v4
	v_mov_b32_e32 v51, v4
	v_mov_b32_e32 v60, v4
	v_mov_b32_e32 v61, v4
	v_mov_b32_e32 v62, v4
	v_mov_b32_e32 v63, v4
	v_mov_b32_e32 v68, v4
	v_mov_b32_e32 v69, v4
	v_mov_b32_e32 v70, v4
	v_mov_b32_e32 v71, v4
	v_mov_b32_e32 v72, v4
	v_mov_b32_e32 v73, v4
	v_mov_b32_e32 v74, v4
	v_mov_b32_e32 v75, v4
	v_mov_b32_e32 v80, v4
	v_mov_b32_e32 v81, v4
	v_mov_b32_e32 v82, v4
	v_mov_b32_e32 v83, v4
	v_mov_b32_e32 v88, v4
	v_mov_b32_e32 v89, v4
	v_mov_b32_e32 v90, v4
	v_mov_b32_e32 v91, v4
	v_mov_b32_e32 v96, v4
	v_mov_b32_e32 v97, v4
	v_mov_b32_e32 v98, v4
	v_mov_b32_e32 v99, v4
	v_mov_b32_e32 v104, v4
	v_mov_b32_e32 v105, v4
	v_mov_b32_e32 v106, v4
	v_mov_b32_e32 v107, v4
	v_mov_b32_e32 v112, v4
	v_mov_b32_e32 v113, v4
	v_mov_b32_e32 v114, v4
	v_mov_b32_e32 v115, v4
	v_mov_b32_e32 v120, v4
	v_mov_b32_e32 v121, v4
	v_mov_b32_e32 v122, v4
	v_mov_b32_e32 v123, v4
	v_mov_b32_e32 v64, v4
	v_mov_b32_e32 v65, v4
	v_mov_b32_e32 v66, v4
	v_mov_b32_e32 v67, v4
	v_mov_b32_e32 v76, v4
	v_mov_b32_e32 v77, v4
	v_mov_b32_e32 v78, v4
	v_mov_b32_e32 v79, v4
	v_mov_b32_e32 v84, v4
	v_mov_b32_e32 v85, v4
	v_mov_b32_e32 v86, v4
	v_mov_b32_e32 v87, v4
	v_mov_b32_e32 v92, v4
	v_mov_b32_e32 v93, v4
	v_mov_b32_e32 v94, v4
	v_mov_b32_e32 v95, v4
	v_mov_b32_e32 v100, v4
	v_mov_b32_e32 v101, v4
	v_mov_b32_e32 v102, v4
	v_mov_b32_e32 v103, v4
	v_mov_b32_e32 v108, v4
	v_mov_b32_e32 v109, v4
	v_mov_b32_e32 v110, v4
	v_mov_b32_e32 v111, v4
	v_mov_b32_e32 v116, v4
	v_mov_b32_e32 v117, v4
	v_mov_b32_e32 v118, v4
	v_mov_b32_e32 v119, v4
	v_mov_b32_e32 v124, v4
	v_mov_b32_e32 v125, v4
	v_mov_b32_e32 v126, v4
	v_mov_b32_e32 v127, v4
	.p2alignl 6, 3212836864
